# v48 + P1 epilogues staggered too (EpiProj's internal barrier pairs with the other half's K-loop barrier)
# baseline (speedup 1.0000x reference)
.Lpeel_done_0:
	v_readlane_b32 s10, v254, 27
	v_readlane_b32 s11, v254, 28
	s_and_b64 s[10:11], s[10:11], s[8:9]
	s_and_b64 vcc, exec, s[10:11]
	s_cbranch_vccz .LBB0_270
	s_barrier
	s_cmp_lt_i32 s18, 0
	s_mov_b64 s[10:11], -1
	s_cbranch_scc1 .LBB0_271

.LBB0_373:
	s_and_b64 vcc, exec, s[2:3]
	s_cbranch_vccnz .LBB0_245
	s_nop 0
	s_branch .LBB0_245
